# v82: neighbourhood-attention window chunk: the K-fragment, relative-position-bias and V-fragment gathers issued in batches instead of one drained load at a time
# baseline (speedup 1.0000x reference)
.LBB0_9:
	s_mul_i32 s3, s6, 3
	s_getpc_b64 s[0:1]
	s_add_u32 s0, s0, PROG@rel32@lo+4
	s_addc_u32 s1, s1, PROG@rel32@hi+12
	s_and_b32 s2, s3, -4
	s_add_u32 s0, s0, s2
	s_addc_u32 s1, s1, 0
	s_load_dwordx2 s[0:1], s[0:1], 0x0
	s_and_b32 s3, s3, 3
	s_lshl_b32 s3, s3, 3
	s_waitcnt lgkmcnt(0)
	s_lshr_b64 s[0:1], s[0:1], s3
	s_and_b32 s2, s0, 0xffff
	v_mov_b32_e32 v0, s2
	s_bfe_u32 s2, s0, 0x80010
	v_mov_b32_e32 v2, s2
	s_cmp_gt_u32 s6, 1
	s_cbranch_scc1 .Lsm_done
	v_readlane_b32 s0, v254, 39
	v_readlane_b32 s1, v254, 40
	s_add_u32 s0, s0, 0xc000
	s_addc_u32 s1, s1, 0
	s_cmp_eq_u32 s6, 1
	s_cbranch_scc1 .Lsm_cache
	s_getreg_b32 s2, hwreg(HW_REG_XCC_ID, 0, 4)
	s_and_b32 s2, s2, 15
	s_lshl_b32 s2, 1, s2
	s_and_b32 s3, s66, 7
	s_lshl_b32 s3, s3, 2
	s_add_u32 s0, s0, s3
	s_addc_u32 s1, s1, 0
	v_mov_b32_e32 v3, s2
	s_mov_b64 s[2:3], exec
	s_mov_b64 exec, 1
	global_atomic_or v1, v3, s[0:1]
	s_mov_b64 exec, s[2:3]
	s_branch .Lsm_done
	s_nop 0
	s_nop 0
.Lsm_cache:
	global_load_dwordx4 v[4:7], v1, s[0:1] sc1
	global_load_dwordx4 v[8:11], v1, s[0:1] offset:16 sc1
	s_waitcnt vmcnt(0)
	v_add_u32_e32 v3, -1, v4
	v_and_b32_e32 v3, v3, v4
	v_add_u32_e32 v4, -1, v5
	v_and_or_b32 v3, v4, v5, v3
	v_add_u32_e32 v4, -1, v6
	v_and_or_b32 v3, v4, v6, v3
	v_add_u32_e32 v4, -1, v7
	v_and_or_b32 v3, v4, v7, v3
	v_add_u32_e32 v4, -1, v8
	v_and_or_b32 v3, v4, v8, v3
	v_add_u32_e32 v4, -1, v9
	v_and_or_b32 v3, v4, v9, v3
	v_add_u32_e32 v4, -1, v10
	v_and_or_b32 v3, v4, v10, v3
	v_add_u32_e32 v4, -1, v11
	v_and_or_b32 v3, v4, v11, v3
	s_nop 0
	v_readfirstlane_b32 s2, v3
	s_nop 1
	v_writelane_b32 v255, s2, 63

.LBB0_33:
	s_add_i32 s36, s40, s50
	s_lshl_b32 s37, s36, 6
	s_add_i32 s62, s48, s37
	s_lshl_b64 s[40:41], s[62:63], 11
	v_lshl_add_u64 v[102:103], v[90:91], 0, s[40:41]
	global_load_dwordx4 v[120:123], v[102:103], off
	global_load_dwordx4 v[124:127], v[102:103], off offset:64
	s_sub_i32 s36, s36, s49
	s_mul_i32 s36, s36, 31
	v_add_co_u32_e32 v164, vcc, 0x2000, v102
	s_nop 1
	v_addc_co_u32_e32 v165, vcc, 0, v103, vcc
	global_load_dwordx4 v[128:131], v[164:165], off
	global_load_dwordx4 v[132:135], v[164:165], off offset:64
	v_add_co_u32_e32 v170, vcc, 0x20000, v102
	s_nop 1
	v_addc_co_u32_e32 v171, vcc, 0, v103, vcc
	global_load_dwordx4 v[136:139], v[170:171], off
	global_load_dwordx4 v[140:143], v[170:171], off offset:64
	v_add_co_u32_e32 v236, vcc, 0x22000, v102
	s_nop 1
	v_addc_co_u32_e32 v237, vcc, 0, v103, vcc
	global_load_dwordx4 v[144:147], v[236:237], off
	global_load_dwordx4 v[148:151], v[236:237], off offset:64
	v_add_co_u32_e32 v238, vcc, 0x40000, v102
	s_nop 1
	v_addc_co_u32_e32 v239, vcc, 0, v103, vcc
	global_load_dwordx4 v[152:155], v[238:239], off
	global_load_dwordx4 v[156:159], v[238:239], off offset:64
	v_add_co_u32_e32 v240, vcc, 0x42000, v102
	s_nop 1
	v_addc_co_u32_e32 v241, vcc, 0, v103, vcc
	global_load_dwordx4 v[160:163], v[240:241], off
	global_load_dwordx4 v[172:175], v[240:241], off offset:64
	v_add_co_u32_e32 v242, vcc, 0x60000, v102
	s_nop 1
	v_addc_co_u32_e32 v243, vcc, 0, v103, vcc
	global_load_dwordx4 v[176:179], v[242:243], off
	global_load_dwordx4 v[180:183], v[242:243], off offset:64
	v_add_co_u32_e32 v244, vcc, 0x62000, v102
	s_nop 1
	v_addc_co_u32_e32 v245, vcc, 0, v103, vcc
	global_load_dwordx4 v[184:187], v[244:245], off
	global_load_dwordx4 v[188:191], v[244:245], off offset:64
	s_waitcnt vmcnt(15)
	v_mfma_f32_16x16x32_bf16 v[54:57], v[120:123], v[2:5], 0
	s_waitcnt vmcnt(13)
	v_mfma_f32_16x16x32_bf16 v[50:53], v[128:131], v[2:5], 0
	s_waitcnt vmcnt(11)
	v_mfma_f32_16x16x32_bf16 v[46:49], v[136:139], v[2:5], 0
	s_waitcnt vmcnt(9)
	v_mfma_f32_16x16x32_bf16 v[42:45], v[144:147], v[2:5], 0
	s_waitcnt vmcnt(7)
	v_mfma_f32_16x16x32_bf16 v[38:41], v[152:155], v[2:5], 0
	s_waitcnt vmcnt(5)
	v_mfma_f32_16x16x32_bf16 v[34:37], v[160:163], v[2:5], 0
	s_waitcnt vmcnt(3)
	v_mfma_f32_16x16x32_bf16 v[26:29], v[176:179], v[2:5], 0
	s_waitcnt vmcnt(1)
	v_mfma_f32_16x16x32_bf16 v[30:33], v[184:187], v[2:5], 0
	v_mfma_f32_16x16x32_bf16 v[54:57], v[124:127], v[6:9], v[54:57]
	v_mfma_f32_16x16x32_bf16 v[50:53], v[132:135], v[6:9], v[50:53]
	v_mfma_f32_16x16x32_bf16 v[46:49], v[140:143], v[6:9], v[46:49]
	v_mfma_f32_16x16x32_bf16 v[42:45], v[148:151], v[6:9], v[42:45]
	v_mfma_f32_16x16x32_bf16 v[38:41], v[156:159], v[6:9], v[38:41]
	v_mfma_f32_16x16x32_bf16 v[34:37], v[172:175], v[6:9], v[34:37]
	v_mfma_f32_16x16x32_bf16 v[26:29], v[180:183], v[6:9], v[26:29]
	s_waitcnt vmcnt(0)
	v_mfma_f32_16x16x32_bf16 v[30:33], v[188:191], v[6:9], v[30:33]
	s_lshl_b32 s100, s62, 1
	s_mov_b32 s101, 0
	v_lshl_add_u64 v[246:247], v[92:93], 0, s[100:101]
	v_add_co_u32_e32 v248, vcc, 0x60000, v246
	s_nop 1
	v_addc_co_u32_e32 v249, vcc, 0, v247, vcc
	v_add_co_u32_e32 v250, vcc, 0xc0000, v246
	s_nop 1
	v_addc_co_u32_e32 v251, vcc, 0, v247, vcc
	v_add_co_u32_e32 v252, vcc, 0x120000, v246
	s_nop 1
	v_addc_co_u32_e32 v253, vcc, 0, v247, vcc
	global_load_dwordx4 v[120:123], v[246:247], off
	global_load_dwordx4 v[124:127], v[246:247], off offset:128
	global_load_dwordx4 v[128:131], v[246:247], off offset:256
	global_load_dwordx4 v[132:135], v[246:247], off offset:384
	global_load_dwordx4 v[136:139], v[248:249], off
	global_load_dwordx4 v[140:143], v[248:249], off offset:128
	global_load_dwordx4 v[144:147], v[248:249], off offset:256
	global_load_dwordx4 v[148:151], v[248:249], off offset:384
	global_load_dwordx4 v[152:155], v[250:251], off
	global_load_dwordx4 v[156:159], v[250:251], off offset:128
	global_load_dwordx4 v[160:163], v[250:251], off offset:256
	global_load_dwordx4 v[172:175], v[250:251], off offset:384
	global_load_dwordx4 v[176:179], v[252:253], off
	global_load_dwordx4 v[180:183], v[252:253], off offset:128
	global_load_dwordx4 v[184:187], v[252:253], off offset:256
	global_load_dwordx4 v[188:191], v[252:253], off offset:384
	s_ashr_i32 s37, s36, 31
	s_lshl_b64 s[36:37], s[36:37], 2
	s_add_u32 s36, s46, s36
	s_addc_u32 s37, s47, s37
	v_lshlrev_b32_e32 v104, 2, v66
	v_lshlrev_b32_e32 v105, 2, v68
	v_lshlrev_b32_e32 v106, 2, v70
	v_lshlrev_b32_e32 v108, 2, v72
	v_lshlrev_b32_e32 v109, 2, v74
	v_lshlrev_b32_e32 v110, 2, v76
	v_lshlrev_b32_e32 v111, 2, v78
	v_lshlrev_b32_e32 v112, 2, v80
	global_load_dword v192, v104, s[36:37] offset:868
	global_load_dword v193, v105, s[36:37] offset:868
	global_load_dword v194, v106, s[36:37] offset:868
	global_load_dword v195, v108, s[36:37] offset:868
	global_load_dword v196, v109, s[36:37] offset:868
	global_load_dword v197, v110, s[36:37] offset:868
	global_load_dword v198, v111, s[36:37] offset:868
	global_load_dword v199, v112, s[36:37] offset:868
	global_load_dword v200, v104, s[36:37] offset:992
	global_load_dword v201, v105, s[36:37] offset:992
	global_load_dword v202, v106, s[36:37] offset:992
	global_load_dword v203, v108, s[36:37] offset:992
	global_load_dword v204, v109, s[36:37] offset:992
	global_load_dword v205, v110, s[36:37] offset:992
	global_load_dword v206, v111, s[36:37] offset:992
	global_load_dword v207, v112, s[36:37] offset:992
	global_load_dword v208, v104, s[36:37] offset:1116
	global_load_dword v209, v105, s[36:37] offset:1116
	global_load_dword v210, v106, s[36:37] offset:1116
	global_load_dword v211, v108, s[36:37] offset:1116
	global_load_dword v212, v109, s[36:37] offset:1116
	global_load_dword v213, v110, s[36:37] offset:1116
	global_load_dword v214, v111, s[36:37] offset:1116
	global_load_dword v215, v112, s[36:37] offset:1116
	global_load_dword v216, v104, s[36:37] offset:1240
	global_load_dword v217, v105, s[36:37] offset:1240
	global_load_dword v218, v106, s[36:37] offset:1240
	global_load_dword v219, v108, s[36:37] offset:1240
	global_load_dword v220, v109, s[36:37] offset:1240
	global_load_dword v221, v110, s[36:37] offset:1240
	global_load_dword v222, v111, s[36:37] offset:1240
	global_load_dword v223, v112, s[36:37] offset:1240
	s_waitcnt vmcnt(28)
	v_add_f32_e32 v192, v54, v192
	v_cndmask_b32_e64 v102, v227, v192, s[16:17]
	v_add_f32_e32 v193, v55, v193
	v_cndmask_b32_e64 v103, v227, v193, s[18:19]
	v_add_f32_e32 v194, v56, v194
	v_cndmask_b32_e64 v54, v227, v194, s[20:21]
	v_add_f32_e32 v195, v57, v195
	v_cndmask_b32_e64 v56, v227, v195, s[24:25]
	s_waitcnt vmcnt(24)
	v_add_f32_e32 v196, v50, v196
	v_cndmask_b32_e64 v55, v227, v196, s[26:27]
	v_add_f32_e32 v197, v51, v197
	v_cndmask_b32_e64 v57, v227, v197, s[28:29]
	v_add_f32_e32 v198, v52, v198
	v_cndmask_b32_e64 v50, v227, v198, s[30:31]
	v_add_f32_e32 v199, v53, v199
	v_cndmask_b32_e64 v52, v227, v199, s[6:7]
	s_waitcnt vmcnt(20)
	v_add_f32_e32 v200, v46, v200
	v_cndmask_b32_e64 v51, v227, v200, s[16:17]
	v_add_f32_e32 v201, v47, v201
	v_cndmask_b32_e64 v53, v227, v201, s[18:19]
	v_add_f32_e32 v202, v48, v202
	v_cndmask_b32_e64 v46, v227, v202, s[20:21]
	v_add_f32_e32 v203, v49, v203
	v_cndmask_b32_e64 v48, v227, v203, s[24:25]
	s_waitcnt vmcnt(16)
	v_add_f32_e32 v204, v42, v204
	v_cndmask_b32_e64 v47, v227, v204, s[26:27]
	v_add_f32_e32 v205, v43, v205
	v_cndmask_b32_e64 v49, v227, v205, s[28:29]
	v_add_f32_e32 v206, v44, v206
	v_cndmask_b32_e64 v42, v227, v206, s[30:31]
	v_add_f32_e32 v207, v45, v207
	v_cndmask_b32_e64 v44, v227, v207, s[6:7]
	s_waitcnt vmcnt(12)
	v_add_f32_e32 v208, v38, v208
	v_cndmask_b32_e64 v43, v227, v208, s[16:17]
	v_add_f32_e32 v209, v39, v209
	v_cndmask_b32_e64 v107, v227, v209, s[18:19]
	v_add_f32_e32 v210, v40, v210
	v_cndmask_b32_e64 v45, v227, v210, s[20:21]
	v_add_f32_e32 v211, v41, v211
	v_cndmask_b32_e64 v40, v227, v211, s[24:25]
	s_waitcnt vmcnt(8)
	v_add_f32_e32 v212, v34, v212
	v_cndmask_b32_e64 v39, v227, v212, s[26:27]
	v_add_f32_e32 v213, v35, v213
	v_cndmask_b32_e64 v41, v227, v213, s[28:29]
	v_add_f32_e32 v214, v36, v214
	v_cndmask_b32_e64 v34, v227, v214, s[30:31]
	v_add_f32_e32 v215, v37, v215
	v_cndmask_b32_e64 v36, v227, v215, s[6:7]
	s_waitcnt vmcnt(4)
	v_add_f32_e32 v216, v26, v216
	v_cndmask_b32_e64 v35, v227, v216, s[16:17]
	v_add_f32_e32 v217, v27, v217
	v_cndmask_b32_e64 v37, v227, v217, s[18:19]
	v_add_f32_e32 v218, v28, v218
	v_cndmask_b32_e64 v26, v227, v218, s[20:21]
	v_add_f32_e32 v219, v29, v219
	v_cndmask_b32_e64 v28, v227, v219, s[24:25]
	s_waitcnt vmcnt(0)
	v_add_f32_e32 v220, v30, v220
	v_cndmask_b32_e64 v27, v227, v220, s[26:27]
	v_add_f32_e32 v221, v31, v221
	v_cndmask_b32_e64 v30, v227, v221, s[28:29]
	v_add_f32_e32 v222, v32, v222
	v_cndmask_b32_e64 v29, v227, v222, s[30:31]
	v_add_f32_e32 v223, v33, v223
	v_cndmask_b32_e64 v31, v227, v223, s[6:7]
	v_max_f32_e32 v32, v56, v56
	v_max_f32_e32 v33, v54, v54
	v_max_f32_e32 v32, v33, v32
	v_max_f32_e32 v33, v52, v52
	v_max_f32_e32 v38, v50, v50
	v_max_f32_e32 v33, v38, v33
	v_max3_f32 v32, v102, v103, v32
	v_max3_f32 v33, v55, v57, v33
	v_max3_f32 v32, v32, s89, v33
	v_max_f32_e32 v33, v48, v48
	v_max_f32_e32 v38, v46, v46
	v_max_f32_e32 v33, v38, v33
	v_max_f32_e32 v38, v44, v44
	v_max_f32_e32 v104, v42, v42
	v_max_f32_e32 v38, v104, v38
	v_max3_f32 v33, v51, v53, v33
	v_max3_f32 v38, v47, v49, v38
	v_max3_f32 v32, v32, v33, v38
	v_max_f32_e32 v33, v40, v40
	v_max_f32_e32 v38, v45, v45
	v_max_f32_e32 v33, v38, v33
	v_max_f32_e32 v38, v36, v36
	v_max_f32_e32 v104, v34, v34
	v_max_f32_e32 v38, v104, v38
	v_max3_f32 v33, v43, v107, v33
	v_max3_f32 v38, v39, v41, v38
	v_max3_f32 v32, v32, v33, v38
	v_max_f32_e32 v33, v28, v28
	v_max_f32_e32 v38, v26, v26
	v_max_f32_e32 v33, v38, v33
	v_max_f32_e32 v38, v31, v31
	v_max_f32_e32 v104, v29, v29
	v_max_f32_e32 v38, v104, v38
	v_max3_f32 v33, v35, v37, v33
	v_max3_f32 v38, v27, v30, v38
	v_max3_f32 v32, v32, v33, v38
	ds_bpermute_b32 v33, v97, v32
	s_lshl_b32 s62, s62, 1
	s_xor_b64 s[36:37], s[38:39], -1
	s_mov_b32 s38, 0xc0000
	s_mov_b32 s40, 4
	s_waitcnt lgkmcnt(0)
	v_max_f32_e32 v33, v33, v33
	v_max_f32_e32 v32, v32, v33
	ds_bpermute_b32 v33, v98, v32
	s_waitcnt lgkmcnt(0)
	v_max3_f32 v38, v0, v32, v33
	v_sub_f32_e32 v33, v103, v38
	v_mul_f32_e32 v33, 0x3fb8aa3b, v33
	v_exp_f32_e32 v109, v33
	v_sub_f32_e32 v33, v54, v38
	v_mul_f32_e32 v33, 0x3fb8aa3b, v33
	v_exp_f32_e32 v110, v33
	v_sub_f32_e32 v33, v56, v38
	v_mul_f32_e32 v33, 0x3fb8aa3b, v33
	v_exp_f32_e32 v111, v33
	v_sub_f32_e32 v33, v55, v38
	v_mul_f32_e32 v33, 0x3fb8aa3b, v33
	v_exp_f32_e32 v112, v33
	v_sub_f32_e32 v33, v57, v38
	v_mul_f32_e32 v33, 0x3fb8aa3b, v33
	v_exp_f32_e32 v113, v33
	v_sub_f32_e32 v33, v50, v38
	v_mul_f32_e32 v33, 0x3fb8aa3b, v33
	v_exp_f32_e32 v114, v33
	v_sub_f32_e32 v33, v52, v38
	v_mul_f32_e32 v33, 0x3fb8aa3b, v33
	v_exp_f32_e32 v115, v33
	v_sub_f32_e32 v33, v51, v38
	v_mul_f32_e32 v33, 0x3fb8aa3b, v33
	v_exp_f32_e32 v55, v33
	v_sub_f32_e32 v33, v53, v38
	v_mul_f32_e32 v33, 0x3fb8aa3b, v33
	v_exp_f32_e32 v56, v33
	v_sub_f32_e32 v33, v46, v38
	v_mul_f32_e32 v33, 0x3fb8aa3b, v33
	v_exp_f32_e32 v57, v33
	v_sub_f32_e32 v33, v48, v38
	v_sub_f32_e32 v0, v0, v38
	v_mul_f32_e32 v33, 0x3fb8aa3b, v33
	v_mul_f32_e32 v32, 0x3fb8aa3b, v0
	v_sub_f32_e32 v0, v102, v38
	v_exp_f32_e32 v102, v33
	v_sub_f32_e32 v33, v47, v38
	v_mul_f32_e32 v33, 0x3fb8aa3b, v33
	v_exp_f32_e32 v103, v33
	v_sub_f32_e32 v33, v49, v38
	v_mul_f32_e32 v33, 0x3fb8aa3b, v33
	v_exp_f32_e32 v104, v33
	v_sub_f32_e32 v33, v42, v38
	v_mul_f32_e32 v33, 0x3fb8aa3b, v33
	v_exp_f32_e32 v105, v33
	v_sub_f32_e32 v33, v44, v38
	v_mul_f32_e32 v33, 0x3fb8aa3b, v33
	v_exp_f32_e32 v106, v33
	v_sub_f32_e32 v33, v43, v38
	v_mul_f32_e32 v33, 0x3fb8aa3b, v33
	v_exp_f32_e32 v47, v33
	v_sub_f32_e32 v33, v107, v38
	v_mul_f32_e32 v33, 0x3fb8aa3b, v33
	v_exp_f32_e32 v48, v33
	v_sub_f32_e32 v33, v45, v38
	v_mul_f32_e32 v33, 0x3fb8aa3b, v33
	v_exp_f32_e32 v49, v33
	v_sub_f32_e32 v33, v40, v38
	v_mul_f32_e32 v33, 0x3fb8aa3b, v33
	v_exp_f32_e32 v50, v33
	v_sub_f32_e32 v33, v39, v38
	v_mul_f32_e32 v33, 0x3fb8aa3b, v33
	v_exp_f32_e32 v51, v33
	v_sub_f32_e32 v33, v41, v38
	v_sub_f32_e32 v26, v26, v38
	v_mul_f32_e32 v33, 0x3fb8aa3b, v33
	v_mul_f32_e32 v26, 0x3fb8aa3b, v26
	v_exp_f32_e32 v52, v33
	v_sub_f32_e32 v33, v34, v38
	v_exp_f32_e32 v41, v26
	v_sub_f32_e32 v26, v28, v38
	v_mul_f32_e32 v33, 0x3fb8aa3b, v33
	v_mul_f32_e32 v26, 0x3fb8aa3b, v26
	v_exp_f32_e32 v53, v33
	v_sub_f32_e32 v33, v36, v38
	v_exp_f32_e32 v42, v26
	v_sub_f32_e32 v26, v27, v38
	v_mul_f32_e32 v33, 0x3fb8aa3b, v33
	v_mul_f32_e32 v26, 0x3fb8aa3b, v26
	v_exp_f32_e32 v54, v33
	v_sub_f32_e32 v33, v35, v38
	v_exp_f32_e32 v43, v26
	v_sub_f32_e32 v26, v30, v38
	v_exp_f32_e32 v34, v32
	v_mul_f32_e32 v33, 0x3fb8aa3b, v33
	v_mul_f32_e32 v26, 0x3fb8aa3b, v26
	v_exp_f32_e32 v39, v33
	v_sub_f32_e32 v33, v37, v38
	v_exp_f32_e32 v44, v26
	v_sub_f32_e32 v26, v29, v38
	v_mul_f32_e32 v33, 0x3fb8aa3b, v33
	v_mul_f32_e32 v26, 0x3fb8aa3b, v26
	s_nop 0
	v_exp_f32_e32 v40, v33
	v_exp_f32_e32 v45, v26
	v_sub_f32_e32 v26, v31, v38
	v_pk_mul_f32 v[32:33], v[12:13], v[34:35] op_sel_hi:[1,0]
	v_pk_mul_f32 v[30:31], v[10:11], v[34:35] op_sel_hi:[1,0]
	v_pk_mul_f32 v[12:13], v[24:25], v[34:35] op_sel_hi:[1,0]
	v_pk_mul_f32 v[10:11], v[22:23], v[34:35] op_sel_hi:[1,0]
	s_nop 0
	v_mul_f32_e32 v0, 0x3fb8aa3b, v0
	v_exp_f32_e32 v108, v0
	v_mul_f32_e32 v26, 0x3fb8aa3b, v26
	v_exp_f32_e32 v46, v26
	v_pk_mul_f32 v[28:29], v[16:17], v[34:35] op_sel_hi:[1,0]
	v_add_f32_e32 v0, 0, v108
	v_add_f32_e32 v0, v109, v0
	v_add_f32_e32 v0, v110, v0
	v_add_f32_e32 v0, v111, v0
	v_add_f32_e32 v0, v112, v0
	v_add_f32_e32 v0, v113, v0
	v_add_f32_e32 v0, v114, v0
	v_add_f32_e32 v0, v115, v0
	v_add_f32_e32 v0, v55, v0
	v_add_f32_e32 v0, v56, v0
	v_add_f32_e32 v0, v57, v0
	v_add_f32_e32 v0, v102, v0
	v_add_f32_e32 v0, v103, v0
	v_add_f32_e32 v0, v104, v0
	v_add_f32_e32 v0, v105, v0
	v_add_f32_e32 v0, v106, v0
	v_add_f32_e32 v0, v47, v0
	v_add_f32_e32 v0, v48, v0
	v_add_f32_e32 v0, v49, v0
	v_add_f32_e32 v0, v50, v0
	v_add_f32_e32 v0, v51, v0
	v_add_f32_e32 v0, v52, v0
	v_add_f32_e32 v0, v53, v0
	v_add_f32_e32 v0, v54, v0
	v_add_f32_e32 v0, v39, v0
	v_add_f32_e32 v0, v40, v0
	v_add_f32_e32 v0, v41, v0
	v_add_f32_e32 v0, v42, v0
	v_add_f32_e32 v0, v43, v0
	v_add_f32_e32 v0, v44, v0
	v_add_f32_e32 v0, v45, v0
	v_add_f32_e32 v0, v46, v0
	v_fmac_f32_e32 v0, v101, v34
	v_pk_mul_f32 v[26:27], v[14:15], v[34:35] op_sel_hi:[1,0]
	v_pk_mul_f32 v[20:21], v[20:21], v[34:35] op_sel_hi:[1,0]
	v_pk_mul_f32 v[18:19], v[18:19], v[34:35] op_sel_hi:[1,0]
	s_nop 0
	v_cvt_pk_bf16_f32 v14, v108, v109
	v_cvt_pk_bf16_f32 v15, v110, v111
	v_cvt_pk_bf16_f32 v16, v112, v113
	v_cvt_pk_bf16_f32 v17, v114, v115
	s_nop 0
	s_waitcnt vmcnt(0)
	v_mfma_f32_16x16x32_bf16 v[22:25], v[120:123], v[14:17], v[30:33]
	s_nop 2
	s_nop 0
	s_waitcnt vmcnt(0)
	v_mfma_f32_16x16x32_bf16 v[26:29], v[136:139], v[14:17], v[26:29]
	s_nop 0
	s_mov_b32 s38, 0x120000
	s_nop 0
	s_nop 0
	s_nop 0
	s_nop 0
	s_mov_b64 s[38:39], 0
	s_nop 0
	s_nop 0
	s_andn2_b64 vcc, exec, s[36:37]
	s_waitcnt vmcnt(0)
	v_mfma_f32_16x16x32_bf16 v[18:21], v[152:155], v[14:17], v[18:21]
	s_nop 0
	s_waitcnt vmcnt(0)
	v_mfma_f32_16x16x32_bf16 v[10:13], v[176:179], v[14:17], v[10:13]
	v_cvt_pk_bf16_f32 v15, v57, v102
	v_cvt_pk_bf16_f32 v16, v103, v104
	v_cvt_pk_bf16_f32 v17, v105, v106
	s_nop 0
	v_cvt_pk_bf16_f32 v14, v55, v56
	s_waitcnt vmcnt(0)
	s_nop 0
	v_mfma_f32_16x16x32_bf16 v[22:25], v[124:127], v[14:17], v[22:25]
	s_nop 0
	s_waitcnt vmcnt(0)
	v_mfma_f32_16x16x32_bf16 v[26:29], v[140:143], v[14:17], v[26:29]
	s_nop 0
	s_waitcnt vmcnt(0)
	v_mfma_f32_16x16x32_bf16 v[18:21], v[156:159], v[14:17], v[18:21]
	s_nop 0
	s_waitcnt vmcnt(0)
	v_mfma_f32_16x16x32_bf16 v[10:13], v[180:183], v[14:17], v[10:13]
	v_cvt_pk_bf16_f32 v14, v47, v48
	v_cvt_pk_bf16_f32 v15, v49, v50
	v_cvt_pk_bf16_f32 v16, v51, v52
	s_nop 0
	v_cvt_pk_bf16_f32 v17, v53, v54
	s_waitcnt vmcnt(0)
	s_nop 0
	v_mfma_f32_16x16x32_bf16 v[48:51], v[128:131], v[14:17], v[22:25]
	s_nop 2
	s_nop 0
	s_waitcnt vmcnt(0)
	v_mfma_f32_16x16x32_bf16 v[52:55], v[144:147], v[14:17], v[26:29]
	s_nop 0
	s_nop 1
	v_cvt_pk_bf16_f32 v26, v39, v40
	v_cvt_pk_bf16_f32 v27, v41, v42
	s_waitcnt vmcnt(0)
	v_mfma_f32_16x16x32_bf16 v[18:21], v[160:163], v[14:17], v[18:21]
	s_nop 0
	v_cvt_pk_bf16_f32 v28, v43, v44
	v_cvt_pk_bf16_f32 v29, v45, v46
	s_waitcnt vmcnt(0)
	v_mfma_f32_16x16x32_bf16 v[22:25], v[184:187], v[14:17], v[10:13]
	s_nop 0
	s_nop 1
	s_nop 0
	s_nop 0
	s_nop 0
	s_waitcnt vmcnt(0)
	v_mfma_f32_16x16x32_bf16 v[18:21], v[172:175], v[26:29], v[18:21]
	s_nop 0
	v_mfma_f32_16x16x32_bf16 v[10:13], v[132:135], v[26:29], v[48:51]
	v_mfma_f32_16x16x32_bf16 v[14:17], v[148:151], v[26:29], v[52:55]
	s_waitcnt vmcnt(0)
	v_mfma_f32_16x16x32_bf16 v[22:25], v[188:191], v[26:29], v[22:25]
	s_cbranch_vccz .LBB0_99
	v_mov_b32_e32 v101, v0
	v_mov_b32_e32 v0, v38
	s_branch .LBB0_33
